# P0: exactly two weight-copy items per wave; the last 128 w_fc2 items move to P2's idle-CU window
# speedup vs baseline: 1.0042x; 1.0031x over previous
.LBB0_44:
	s_add_i32 s98, s98, s34
	s_cmpk_gt_i32 s98, 0xfff
	s_cbranch_scc1 .LBB0_83
	s_cmpk_lt_i32 s98, 0x880
	s_cselect_b32 s14, 0, 0xc00
	s_add_i32 s14, s14, s98

.Lxp_fc1_done:
	v_readlane_b32 s12, v254, 4
	v_readlane_b32 s13, v254, 5
	s_add_u32 s14, s78, 0x1600000
	s_addc_u32 s15, s79, 0
	v_and_b32_e32 v0, 63, v210
	v_and_b32_e32 v1, 7, v0
	v_lshrrev_b32_e32 v2, 3, v0
	v_mul_u32_u24_e32 v3, 0x8000, v2
	v_lshl_add_u32 v3, v1, 4, v3
	v_and_b32_e32 v4, 1, v1
	v_lshlrev_b32_e32 v4, 4, v4
	v_lshrrev_b32_e32 v5, 1, v1
	v_lshl_add_u32 v4, v5, 2, v4
	v_mul_u32_u24_e32 v4, 0x2000, v4
	v_lshl_add_u32 v4, v2, 4, v4
	v_add_u32_e32 v5, 0x2000, v4
	v_add_u32_e32 v6, 0x4000, v4
	v_add_u32_e32 v7, 0x6000, v4
	s_add_i32 s35, s37, 0x780
	s_cmp_ge_u32 s35, 2048
	s_cbranch_scc1 .Lxp_fc2t_done
.Lxp_fc2t_loop:
	s_lshr_b32 s0, s35, 5
	s_and_b32 s1, s35, 31
	s_mul_i32 s3, s0, 0x40000
	s_lshl_b32 s20, s1, 7
	s_add_u32 s3, s3, s20
	s_add_u32 s8, s12, s3
	s_addc_u32 s9, s13, 0
	s_lshl_b32 s20, s1, 5
	s_and_b32 s21, s20, 0xffffff00
	s_bfe_u32 s3, s20, 0x10005
	s_lshl_b32 s3, s3, 7
	s_add_i32 s21, s21, s3
	s_bfe_u32 s3, s20, 0x20006
	s_lshl_b32 s3, s3, 5
	s_add_i32 s21, s21, s3
	s_mul_i32 s21, s21, 0x2000
	s_lshl_b32 s3, s0, 7
	s_add_u32 s21, s21, s3
	s_add_u32 s10, s14, s21
	s_addc_u32 s11, s15, 0
	global_load_dwordx4 v[16:19], v3, s[8:9]
	s_add_u32 s8, s8, 0x1000
	s_addc_u32 s9, s9, 0
	global_load_dwordx4 v[20:23], v3, s[8:9]
	s_add_u32 s8, s8, 0x1000
	s_addc_u32 s9, s9, 0
	global_load_dwordx4 v[24:27], v3, s[8:9]
	s_add_u32 s8, s8, 0x1000
	s_addc_u32 s9, s9, 0
	global_load_dwordx4 v[28:31], v3, s[8:9]
	s_add_u32 s8, s8, 0x1000
	s_addc_u32 s9, s9, 0
	global_load_dwordx4 v[32:35], v3, s[8:9]
	s_add_u32 s8, s8, 0x1000
	s_addc_u32 s9, s9, 0
	global_load_dwordx4 v[36:39], v3, s[8:9]
	s_add_u32 s8, s8, 0x1000
	s_addc_u32 s9, s9, 0
	global_load_dwordx4 v[40:43], v3, s[8:9]
	s_add_u32 s8, s8, 0x1000
	s_addc_u32 s9, s9, 0
	global_load_dwordx4 v[44:47], v3, s[8:9]
	s_waitcnt vmcnt(0)
	v_cvt_pk_bf16_f32 v48, v16, v20
	v_cvt_pk_bf16_f32 v49, v24, v28
	v_cvt_pk_bf16_f32 v50, v32, v36
	v_cvt_pk_bf16_f32 v51, v40, v44
	v_cvt_pk_bf16_f32 v52, v17, v21
	v_cvt_pk_bf16_f32 v53, v25, v29
	v_cvt_pk_bf16_f32 v54, v33, v37
	v_cvt_pk_bf16_f32 v55, v41, v45
	v_cvt_pk_bf16_f32 v56, v18, v22
	v_cvt_pk_bf16_f32 v57, v26, v30
	v_cvt_pk_bf16_f32 v58, v34, v38
	v_cvt_pk_bf16_f32 v59, v42, v46
	v_cvt_pk_bf16_f32 v60, v19, v23
	v_cvt_pk_bf16_f32 v61, v27, v31
	v_cvt_pk_bf16_f32 v62, v35, v39
	v_cvt_pk_bf16_f32 v63, v43, v47
	global_store_dwordx4 v4, v[48:51], s[10:11]
	global_store_dwordx4 v5, v[52:55], s[10:11]
	global_store_dwordx4 v6, v[56:59], s[10:11]
	global_store_dwordx4 v7, v[60:63], s[10:11]
	s_add_i32 s35, s35, 768
	s_cmp_lt_u32 s35, 2048
	s_cbranch_scc1 .Lxp_fc2t_loop
